# P6 three rotations by XCD slot (bid&7): {0,3,6} up-gate-ple, {1,4,7} gate-ple-up, {2,5} gate-up-ple
# baseline (speedup 1.0000x reference)
; __global__ void __launch_bounds__(512, 2) fwd_mega(Params P) {
;     ...
;     { EpiUp E{(bf16_t*)(ws + OFF_FFB)}; run_gemm(glds, (const bf16_t*)(ws + OFF_H1B), (const bf16_t*)(ws + OFF_WUP), 4096, DM, E, wid_s); }
;     { EpiGate E{(bf16_t*)(ws + OFF_PG), P.in[18]}; run_gemm(glds, (const bf16_t*)(ws + OFF_H1B), (const bf16_t*)(ws + OFF_WG), DM, DM, E, wid_s); }
.Lp6_up_entry:
	s_add_u32 s4, s80, 0x4800000
	v_readlane_b32 s0, v255, 31
	s_addc_u32 s5, s81, 0
	s_lshl_b32 s0, s0, 5
	s_and_b32 s36, s0, 0x60
	s_lshl_b32 s37, s36, 7
	s_cmpk_gt_i32 s33, 0x3ff
	s_waitcnt lgkmcnt(0)
	s_barrier
	v_mbcnt_lo_u32_b32 v8, -1, 0
	v_mbcnt_hi_u32_b32 v8, -1, v8
	s_cbranch_scc1 .LBB0_830
	s_cmp_eq_u32 s98, 0
	s_cbranch_scc0 .Lp6_up_go
	s_and_b32 s99, s33, 7
	s_mov_b32 s100, 0x92
	s_bitcmp1_b32 s100, s99
	s_cbranch_scc0 .Lp6_chk_mid
	s_mov_b32 s98, 1
	s_branch .LBB0_830
.Lp6_chk_mid:
	s_mov_b32 s100, 0x24
	s_bitcmp1_b32 s100, s99
	s_cbranch_scc0 .Lp6_up_go
	s_mov_b32 s98, 4
	s_branch .LBB0_830

; __global__ void __launch_bounds__(512, 2) fwd_mega(Params P) {
;     ...
;     { EpiUp E{(bf16_t*)(ws + OFF_FFB)}; run_gemm(glds, (const bf16_t*)(ws + OFF_H1B), (const bf16_t*)(ws + OFF_WUP), 4096, DM, E, wid_s); }
;     { EpiGate E{(bf16_t*)(ws + OFF_PG), P.in[18]}; run_gemm(glds, (const bf16_t*)(ws + OFF_H1B), (const bf16_t*)(ws + OFF_WG), DM, DM, E, wid_s); }
;     { EpiPle E{(bf16_t*)(ws + OFF_PG)}; run_gemm(glds, (const bf16_t*)(ws + OFF_PB), (const bf16_t*)(ws + OFF_WPLE), DM, 256, E, wid_s); }
.LBB0_830:
	s_cmp_eq_u32 s98, 2
	s_cbranch_scc1 .Lp6_to_b7
	s_cmp_eq_u32 s98, 5
	s_cbranch_scc1 .Lp6_to_ple
	s_add_u32 s6, s80, 0xc800000
	v_cndmask_b32_e64 v0, 0, 1, s[8:9]
	s_addc_u32 s7, s81, 0
	v_cmp_ne_u32_e64 s[0:1], 1, v0
	s_andn2_b64 vcc, exec, s[8:9]
	v_mbcnt_lo_u32_b32 v8, -1, 0
	v_mbcnt_hi_u32_b32 v8, -1, v8
	s_cbranch_vccnz .LBB0_854
	s_ashr_i32 s30, s33, 31
	s_lshr_b32 s2, s30, 29
	s_add_i32 s9, s33, s2
	s_and_b32 s2, s9, -8
	s_sub_i32 s10, s33, s2
	s_cmp_gt_i32 s10, -1
	s_cbranch_scc0 .LBB0_833
	s_lshl_b32 s8, s10, 5
	s_cbranch_execz .LBB0_834
	s_branch .LBB0_835

; __global__ void __launch_bounds__(512, 2) fwd_mega(Params P) {
;     ...
;     { EpiGate E{(bf16_t*)(ws + OFF_PG), P.in[18]}; run_gemm(glds, (const bf16_t*)(ws + OFF_H1B), (const bf16_t*)(ws + OFF_WG), DM, DM, E, wid_s); }
;     { EpiPle E{(bf16_t*)(ws + OFF_PG)}; run_gemm(glds, (const bf16_t*)(ws + OFF_PB), (const bf16_t*)(ws + OFF_WPLE), DM, 256, E, wid_s); }
;     xcd_barrier(xbar, wid_s);
.LBB0_854:
	s_cmp_eq_u32 s98, 4
	s_cbranch_scc0 .Lp6_ple_go
	s_mov_b32 s98, 5
	s_branch .Lp6_up_entry
.Lp6_to_ple:
	s_add_u32 s6, s80, 0xc800000
	s_addc_u32 s7, s81, 0
	s_cmpk_gt_i32 s33, 0xff
	s_cselect_b64 s[0:1], -1, 0
	s_mov_b32 s98, 6
